# attention key loops: cross-half row-max exchange by v_permlane32_swap instead of ds_bpermute+lgkmcnt(0) (DSA head, fox head x2); DSA score-register copies and row-sum update moved in front of the loop
# baseline (speedup 1.0000x reference)
; #define AT_STAGE(tile) do { const int _i = (tile) < nkt ? (tile) : (nkt - 1); const int _t = AT_TILE(_i); char* _s = dynsmem + ((tile) & 3) * 32768 + tid * 16; \
;     const u16* _kg = Kg0 + (size_t)_t * 64 * ldk; const u16* _vg = Vg0 + _t * 64; \
;     AT_GLDS(_kg, _s); AT_GLDS(_kg + k32, _s + 8192); AT_GLDS(_vg, _s + 16384); AT_GLDS(_vg + v64, _s + 16384 + 8192); } while (0)
; template <int MODE>
; DI void attn_item(const u16* Qp, int ldq, const u16* Kp, int ldk, const u16* VTp, int ldv, u16* Op, int ldo,
;                   int q0, int nkt, const float* Fc, const unsigned* BM, float kmaxn, char* smem) {
;     ...
;   for (int kt = 0; kt < nkt; ++kt) {
;     const char* sKn = smem + ((kt + 1) & 3) * 32768;
;     const char* sV = smem + (kt & 3) * 32768 + 16384;
;     const float* sF = fct + (kt & 3) * 64;
;     const int ts = AT_TILE(kt) * 64;
;     const bool more1 = (kt + 1 < nkt);
;     uint2 bwn = make_uint2(0xffffffffu, 0xffffffffu);
;     const int tn = AT_TILE(more1 ? (kt + 1) : kt);
;     float flast = 0.f;
;     if (MODE == 1) { rf = *(const f32x4*)(Fc + tn * 64 + (tid & 15) * 4); flast = Fc[tn * 64 + 63]; }
;     if (MODE == 2) bwn = *(const uint2*)(bmq + tn * 2);
;     AT_STAGE(kt + 3);
;     const bool diag = (MODE == 1) && (ts + 63 > qw);
;     float mx = -1e30f;
;     if (MODE == 1) {
; #pragma unroll
;       for (int k2 = 0; k2 < 2; ++k2)
; #pragma unroll
;         for (int j = 0; j < 4; ++j) {
;           const int kl = 32 * k2 + 16 * (j >> 1) + 8 * h + 4 * (j & 1);
;           const f32x4 f4 = *(const f32x4*)(sF + kl);
; #pragma unroll
;           for (int i = 0; i < 4; ++i) {
;             float x = sc[k2][j * 4 + i] * c1 + (fcq - f4[i]);
;             if (diag && (ts + kl + i > q)) x = -1e30f;
;             sc[k2][j * 4 + i] = x;
;             mx = fmaxf(mx, x);
;           }
;         }
.LBB0_475:
	s_add_i32 s18, s14, 1
	s_and_b32 s15, s14, 3
	s_cmp_lt_i32 s18, s63
	s_cselect_b32 s10, s18, s14
	s_sub_i32 s10, s51, s10
	s_lshl_b32 s10, s10, 6
	s_ashr_i32 s11, s10, 31
	s_lshl_b64 s[10:11], s[10:11], 2
	s_add_u32 s10, s38, s10
	s_addc_u32 s11, s39, s11
	global_load_dwordx4 v[130:133], v142, s[10:11]
	global_load_dword v165, v1, s[10:11] offset:252
	s_add_i32 s10, s14, 3
	s_min_i32 s10, s10, s51
	s_sub_i32 s14, s51, s10
	s_and_b32 s10, s17, 0x18000
	v_add_u32_e32 v170, s10, v144
	v_mad_i64_i32 v[166:167], s[10:11], s14, v211, v[136:137]
	s_lshl_b32 s10, s14, 6
	s_ashr_i32 s11, s10, 31
	v_lshl_add_u64 v[168:169], s[10:11], 1, v[138:139]
	v_readfirstlane_b32 s10, v170
	v_add_u32_e32 v171, 0x2000, v170
	s_mov_b32 m0, s10
	v_readfirstlane_b32 s10, v171
	global_load_lds_dwordx4 v[166:167], off
	v_lshl_add_u64 v[166:167], v[166:167], 0, s[84:85]
	s_mov_b32 m0, s10
	v_add_u32_e32 v171, s16, v0
	global_load_lds_dwordx4 v[166:167], off
	v_add_u32_e32 v166, 0x4000, v170
	v_subrev_u32_e32 v176, 63, v171
	v_readfirstlane_b32 s10, v166
	s_mov_b32 m0, s10
	v_lshl_add_u64 v[166:167], v[168:169], 0, s[86:87]
	global_load_lds_dwordx4 v[168:169], off
	v_add_u32_e32 v168, 0x6000, v170
	v_lshl_add_u32 v170, s15, 8, v162
	v_readfirstlane_b32 s10, v168
	s_mov_b32 m0, s10
	v_cmp_gt_i32_e64 s[10:11], s16, v140
	global_load_lds_dwordx4 v[166:167], off
	ds_read_b128 v[166:169], v170
	ds_read_b128 v[172:175], v170 offset:16
	ds_read_b128 v[212:215], v170 offset:64
	ds_read_b128 v[234:237], v170 offset:80
	ds_read_b128 v[238:241], v170 offset:128
	ds_read_b128 v[242:245], v170 offset:144
	ds_read_b128 v[246:249], v170 offset:192
	ds_read_b128 v[250:253], v170 offset:208
	s_cmp_eq_u64 s[10:11], 0
	s_cbranch_scc1 .Lfox_fast
	v_cmp_gt_i32_e32 vcc, v176, v134
	s_and_b64 vcc, s[10:11], vcc
	s_mov_b32 s14, 0xf149f2ca
	s_waitcnt lgkmcnt(0)
	v_sub_f32_e32 v166, v141, v166
	v_fmac_f32_e32 v166, 0x3e0293ee, v66
	v_sub_f32_e32 v66, v141, v167
	v_cndmask_b32_e32 v185, v166, v219, vcc
	v_fmac_f32_e32 v66, 0x3e0293ee, v67
	v_cmp_ge_i32_e32 vcc, v176, v134
	v_sub_f32_e32 v67, v141, v168
	s_and_b64 vcc, s[10:11], vcc
	v_fmac_f32_e32 v67, 0x3e0293ee, v68
	v_subrev_u32_e32 v68, 61, v171
	v_cndmask_b32_e32 v191, v66, v219, vcc
	v_cmp_gt_i32_e32 vcc, v68, v134
	s_and_b64 vcc, s[10:11], vcc
	v_subrev_u32_e32 v68, 60, v171
	v_cndmask_b32_e32 v192, v67, v219, vcc
	v_sub_f32_e32 v67, v141, v169
	v_cmp_gt_i32_e32 vcc, v68, v134
	v_fmac_f32_e32 v67, 0x3e0293ee, v69
	s_and_b64 vcc, s[10:11], vcc
	v_cndmask_b32_e32 v193, v67, v219, vcc
	v_subrev_u32_e32 v67, 59, v171
	v_sub_f32_e32 v68, v141, v172
	v_cmp_gt_i32_e32 vcc, v67, v134
	v_fmac_f32_e32 v68, 0x3e0293ee, v70
	s_and_b64 vcc, s[10:11], vcc
	v_cndmask_b32_e32 v198, v68, v219, vcc
	v_sub_f32_e32 v68, v141, v173
	v_cmp_ge_i32_e32 vcc, v67, v134
	v_fmac_f32_e32 v68, 0x3e0293ee, v71
	s_and_b64 vcc, s[10:11], vcc
	v_cndmask_b32_e32 v197, v68, v219, vcc
	v_subrev_u32_e32 v68, 57, v171
	v_sub_f32_e32 v67, v141, v174
	v_cmp_gt_i32_e32 vcc, v68, v134
	v_fmac_f32_e32 v67, 0x3e0293ee, v72
	s_and_b64 vcc, s[10:11], vcc
	v_subrev_u32_e32 v68, 56, v171
	v_max3_f32 v66, v185, s14, v191
	v_cndmask_b32_e32 v195, v67, v219, vcc
	v_sub_f32_e32 v67, v141, v175
	v_cmp_gt_i32_e32 vcc, v68, v134
	v_max3_f32 v66, v66, v192, v193
	v_fmac_f32_e32 v67, 0x3e0293ee, v73
	s_and_b64 vcc, s[10:11], vcc
	v_max3_f32 v66, v66, v198, v197
	v_cndmask_b32_e32 v196, v67, v219, vcc
	v_max3_f32 v70, v66, v195, v196
	v_subrev_u32_e32 v71, 47, v171
	v_cmp_gt_i32_e32 vcc, v71, v134
	s_and_b64 vcc, s[10:11], vcc
	s_waitcnt lgkmcnt(0)
	v_sub_f32_e32 v66, v141, v212
	v_fmac_f32_e32 v66, 0x3e0293ee, v74
	v_cndmask_b32_e32 v184, v66, v219, vcc
	v_sub_f32_e32 v66, v141, v213
	v_cmp_ge_i32_e32 vcc, v71, v134
	v_fmac_f32_e32 v66, 0x3e0293ee, v75
	s_and_b64 vcc, s[10:11], vcc
	v_sub_f32_e32 v67, v141, v214
	v_subrev_u32_e32 v68, 45, v171
	v_cndmask_b32_e32 v183, v66, v219, vcc
	v_cmp_gt_i32_e32 vcc, v68, v134
	v_fmac_f32_e32 v67, 0x3e0293ee, v76
	s_and_b64 vcc, s[10:11], vcc
	v_subrev_u32_e32 v68, 44, v171
	v_cndmask_b32_e32 v182, v67, v219, vcc
	v_sub_f32_e32 v67, v141, v215
	v_cmp_gt_i32_e32 vcc, v68, v134
	v_fmac_f32_e32 v67, 0x3e0293ee, v77
	s_and_b64 vcc, s[10:11], vcc
	v_max3_f32 v66, v70, v184, v183
	v_cndmask_b32_e32 v179, v67, v219, vcc
	v_max3_f32 v70, v66, v182, v179
	v_subrev_u32_e32 v71, 43, v171
	v_cmp_gt_i32_e32 vcc, v71, v134
	s_and_b64 vcc, s[10:11], vcc
	s_waitcnt lgkmcnt(0)
	v_sub_f32_e32 v66, v141, v234
	v_fmac_f32_e32 v66, 0x3e0293ee, v78
	v_cndmask_b32_e32 v194, v66, v219, vcc
	v_sub_f32_e32 v66, v141, v235
	v_cmp_ge_i32_e32 vcc, v71, v134
	v_fmac_f32_e32 v66, 0x3e0293ee, v79
	s_and_b64 vcc, s[10:11], vcc
	v_sub_f32_e32 v67, v141, v236
	v_subrev_u32_e32 v68, 41, v171
	v_cndmask_b32_e32 v188, v66, v219, vcc
	v_cmp_gt_i32_e32 vcc, v68, v134
	v_fmac_f32_e32 v67, 0x3e0293ee, v80
	s_and_b64 vcc, s[10:11], vcc
	v_subrev_u32_e32 v68, 40, v171
	v_cndmask_b32_e32 v186, v67, v219, vcc
	v_sub_f32_e32 v67, v141, v237
	v_cmp_gt_i32_e32 vcc, v68, v134
	v_fmac_f32_e32 v67, 0x3e0293ee, v81
	s_and_b64 vcc, s[10:11], vcc
	v_max3_f32 v66, v70, v194, v188
	v_cndmask_b32_e32 v187, v67, v219, vcc
	v_max3_f32 v70, v66, v186, v187
	v_subrev_u32_e32 v71, 31, v171
	v_cmp_gt_i32_e32 vcc, v71, v134
	s_and_b64 vcc, s[10:11], vcc
	s_waitcnt lgkmcnt(0)
; DI float shflx(float v, int m, int lane) { return __int_as_float(__builtin_amdgcn_ds_bpermute((lane ^ m) << 2, __float_as_int(v))); }
; template <int MODE>
; DI void attn_item(const u16* Qp, int ldq, const u16* Kp, int ldk, const u16* VTp, int ldv, u16* Op, int ldo,
;                   int q0, int nkt, const float* Fc, const unsigned* BM, float kmaxn, char* smem) {
;     ...
;     if (MODE == 1) {
; #pragma unroll
;       for (int k2 = 0; k2 < 2; ++k2)
; #pragma unroll
;         for (int j = 0; j < 4; ++j) {
;           const int kl = 32 * k2 + 16 * (j >> 1) + 8 * h + 4 * (j & 1);
;           const f32x4 f4 = *(const f32x4*)(sF + kl);
; #pragma unroll
;           for (int i = 0; i < 4; ++i) {
;             float x = sc[k2][j * 4 + i] * c1 + (fcq - f4[i]);
;             if (diag && (ts + kl + i > q)) x = -1e30f;
;             sc[k2][j * 4 + i] = x;
;             mx = fmaxf(mx, x);
;           }
;         }
;     } else {
; #pragma unroll
;       for (int k2 = 0; k2 < 2; ++k2)
; #pragma unroll
;         for (int e = 0; e < 16; ++e) mx = fmaxf(mx, sc[k2][e]);
;       mx *= c1;
;     }
;     mx = fmaxf(mx, shflx(mx, 32, lane));
;     if (__any(mx > m_run + 8.f)) {
;       const float m_new = fmaxf(m_run, mx);
;       const float alpha = __builtin_amdgcn_exp2f(m_run - m_new);
;       m_run = m_new; l_run *= alpha;
; #pragma unroll
;       for (int i = 0; i < 4; ++i)
; #pragma unroll
;         for (int e = 0; e < 16; ++e) o[i][e] *= alpha;
;     }
	v_sub_f32_e32 v66, v141, v238
	v_fmac_f32_e32 v66, 0x3e0293ee, v82
	v_cndmask_b32_e32 v176, v66, v219, vcc
	v_sub_f32_e32 v66, v141, v239
	v_cmp_ge_i32_e32 vcc, v71, v134
	v_fmac_f32_e32 v66, 0x3e0293ee, v83
	s_and_b64 vcc, s[10:11], vcc
	v_sub_f32_e32 v67, v141, v240
	v_subrev_u32_e32 v68, 29, v171
	v_cndmask_b32_e32 v175, v66, v219, vcc
	v_cmp_gt_i32_e32 vcc, v68, v134
	v_fmac_f32_e32 v67, 0x3e0293ee, v84
	s_and_b64 vcc, s[10:11], vcc
	v_subrev_u32_e32 v68, 28, v171
	v_cndmask_b32_e32 v174, v67, v219, vcc
	v_sub_f32_e32 v67, v141, v241
	v_cmp_gt_i32_e32 vcc, v68, v134
	v_fmac_f32_e32 v67, 0x3e0293ee, v85
	s_and_b64 vcc, s[10:11], vcc
	v_max3_f32 v66, v70, v176, v175
	v_cndmask_b32_e32 v173, v67, v219, vcc
	v_max3_f32 v70, v66, v174, v173
	v_subrev_u32_e32 v71, 27, v171
	v_cmp_gt_i32_e32 vcc, v71, v134
	s_and_b64 vcc, s[10:11], vcc
	s_waitcnt lgkmcnt(0)
	v_sub_f32_e32 v66, v141, v242
	v_fmac_f32_e32 v66, 0x3e0293ee, v86
	v_cndmask_b32_e32 v190, v66, v219, vcc
	v_sub_f32_e32 v66, v141, v243
	v_cmp_ge_i32_e32 vcc, v71, v134
	v_fmac_f32_e32 v66, 0x3e0293ee, v87
	s_and_b64 vcc, s[10:11], vcc
	v_sub_f32_e32 v67, v141, v244
	v_subrev_u32_e32 v68, 25, v171
	v_cndmask_b32_e32 v180, v66, v219, vcc
	v_cmp_gt_i32_e32 vcc, v68, v134
	v_fmac_f32_e32 v67, 0x3e0293ee, v88
	s_and_b64 vcc, s[10:11], vcc
	v_subrev_u32_e32 v68, 24, v171
	v_cndmask_b32_e32 v177, v67, v219, vcc
	v_sub_f32_e32 v67, v141, v245
	v_cmp_gt_i32_e32 vcc, v68, v134
	v_fmac_f32_e32 v67, 0x3e0293ee, v89
	s_and_b64 vcc, s[10:11], vcc
	v_max3_f32 v66, v70, v190, v180
	v_cndmask_b32_e32 v178, v67, v219, vcc
	v_max3_f32 v70, v66, v177, v178
	v_add_u32_e32 v71, -15, v171
	v_cmp_gt_i32_e32 vcc, v71, v134
	s_and_b64 vcc, s[10:11], vcc
	s_waitcnt lgkmcnt(0)
	v_sub_f32_e32 v66, v141, v246
	v_fmac_f32_e32 v66, 0x3e0293ee, v90
	v_cndmask_b32_e32 v169, v66, v219, vcc
	v_sub_f32_e32 v66, v141, v247
	v_cmp_ge_i32_e32 vcc, v71, v134
	v_fmac_f32_e32 v66, 0x3e0293ee, v91
	s_and_b64 vcc, s[10:11], vcc
	v_sub_f32_e32 v67, v141, v248
	v_add_u32_e32 v68, -13, v171
	v_cndmask_b32_e32 v168, v66, v219, vcc
	v_cmp_gt_i32_e32 vcc, v68, v134
	v_fmac_f32_e32 v67, 0x3e0293ee, v92
	s_and_b64 vcc, s[10:11], vcc
	v_add_u32_e32 v68, -12, v171
	v_cndmask_b32_e32 v167, v67, v219, vcc
	v_sub_f32_e32 v67, v141, v249
	v_cmp_gt_i32_e32 vcc, v68, v134
	v_fmac_f32_e32 v67, 0x3e0293ee, v93
	s_and_b64 vcc, s[10:11], vcc
	v_max3_f32 v66, v70, v169, v168
	v_cndmask_b32_e32 v166, v67, v219, vcc
	v_max3_f32 v70, v66, v167, v166
	v_add_u32_e32 v71, -11, v171
	v_cmp_gt_i32_e32 vcc, v71, v134
	s_and_b64 vcc, s[10:11], vcc
	s_waitcnt lgkmcnt(0)
	v_sub_f32_e32 v66, v141, v250
	v_fmac_f32_e32 v66, 0x3e0293ee, v94
	v_cndmask_b32_e32 v181, v66, v219, vcc
	v_sub_f32_e32 v66, v141, v251
	v_cmp_ge_i32_e32 vcc, v71, v134
	v_fmac_f32_e32 v66, 0x3e0293ee, v95
	s_and_b64 vcc, s[10:11], vcc
	v_sub_f32_e32 v67, v141, v252
	v_add_u32_e32 v68, -9, v171
	v_cndmask_b32_e32 v172, v66, v219, vcc
	v_cmp_gt_i32_e32 vcc, v68, v134
	v_fmac_f32_e32 v67, 0x3e0293ee, v96
	s_and_b64 vcc, s[10:11], vcc
	v_add_u32_e32 v68, -8, v171
	v_cndmask_b32_e32 v170, v67, v219, vcc
	v_sub_f32_e32 v67, v141, v253
	v_cmp_gt_i32_e32 vcc, v68, v134
	v_fmac_f32_e32 v67, 0x3e0293ee, v97
	s_and_b64 vcc, s[10:11], vcc
	v_max3_f32 v66, v70, v181, v172
	v_cndmask_b32_e32 v171, v67, v219, vcc
	v_max3_f32 v66, v66, v170, v171
	v_mov_b32_e32 v67, v66
	s_nop 1
	v_permlane32_swap_b32_e32 v67, v66
	s_nop 0
	v_max_f32_e32 v66, v66, v67
	v_add_f32_e32 v67, 0x41000000, v164
	v_cmp_gt_f32_e32 vcc, v66, v67
	s_cbranch_vccz .LBB0_477
	v_max_f32_e32 v66, v66, v66
	v_max_f32_e32 v67, v164, v164
	v_max_f32_e32 v67, v67, v66
	v_sub_f32_e32 v66, v164, v67
	v_exp_f32_e32 v66, v66
	v_mov_b32_e32 v164, v67
	v_pk_mul_f32 v[64:65], v[64:65], v[66:67] op_sel_hi:[1,0]
	v_pk_mul_f32 v[62:63], v[62:63], v[66:67] op_sel_hi:[1,0]
	v_pk_mul_f32 v[60:61], v[60:61], v[66:67] op_sel_hi:[1,0]
	v_pk_mul_f32 v[58:59], v[58:59], v[66:67] op_sel_hi:[1,0]
	v_pk_mul_f32 v[56:57], v[56:57], v[66:67] op_sel_hi:[1,0]
	v_pk_mul_f32 v[54:55], v[54:55], v[66:67] op_sel_hi:[1,0]
	v_pk_mul_f32 v[52:53], v[52:53], v[66:67] op_sel_hi:[1,0]
	v_pk_mul_f32 v[50:51], v[50:51], v[66:67] op_sel_hi:[1,0]
	v_pk_mul_f32 v[48:49], v[48:49], v[66:67] op_sel_hi:[1,0]
	v_pk_mul_f32 v[46:47], v[46:47], v[66:67] op_sel_hi:[1,0]
	v_pk_mul_f32 v[44:45], v[44:45], v[66:67] op_sel_hi:[1,0]
	v_pk_mul_f32 v[42:43], v[42:43], v[66:67] op_sel_hi:[1,0]
	v_pk_mul_f32 v[40:41], v[40:41], v[66:67] op_sel_hi:[1,0]
	v_pk_mul_f32 v[38:39], v[38:39], v[66:67] op_sel_hi:[1,0]
	v_pk_mul_f32 v[36:37], v[36:37], v[66:67] op_sel_hi:[1,0]
	v_pk_mul_f32 v[34:35], v[34:35], v[66:67] op_sel_hi:[1,0]
	v_pk_mul_f32 v[32:33], v[32:33], v[66:67] op_sel_hi:[1,0]
	v_pk_mul_f32 v[30:31], v[30:31], v[66:67] op_sel_hi:[1,0]
	v_pk_mul_f32 v[28:29], v[28:29], v[66:67] op_sel_hi:[1,0]
	v_pk_mul_f32 v[26:27], v[26:27], v[66:67] op_sel_hi:[1,0]
	v_pk_mul_f32 v[24:25], v[24:25], v[66:67] op_sel_hi:[1,0]
	v_pk_mul_f32 v[22:23], v[22:23], v[66:67] op_sel_hi:[1,0]
	v_pk_mul_f32 v[20:21], v[20:21], v[66:67] op_sel_hi:[1,0]
	v_pk_mul_f32 v[18:19], v[18:19], v[66:67] op_sel_hi:[1,0]
	v_pk_mul_f32 v[16:17], v[16:17], v[66:67] op_sel_hi:[1,0]
	v_pk_mul_f32 v[14:15], v[14:15], v[66:67] op_sel_hi:[1,0]
	v_pk_mul_f32 v[12:13], v[12:13], v[66:67] op_sel_hi:[1,0]
	v_pk_mul_f32 v[10:11], v[10:11], v[66:67] op_sel_hi:[1,0]
	v_pk_mul_f32 v[8:9], v[8:9], v[66:67] op_sel_hi:[1,0]
	v_pk_mul_f32 v[6:7], v[6:7], v[66:67] op_sel_hi:[1,0]
	v_pk_mul_f32 v[4:5], v[4:5], v[66:67] op_sel_hi:[1,0]
	v_pk_mul_f32 v[2:3], v[2:3], v[66:67] op_sel_hi:[1,0]
	v_mul_f32_e32 v161, v161, v66

; DI float shflx(float v, int m, int lane) { return __int_as_float(__builtin_amdgcn_ds_bpermute((lane ^ m) << 2, __float_as_int(v))); }
; template <int MODE>
; DI void attn_item(const u16* Qp, int ldq, const u16* Kp, int ldk, const u16* VTp, int ldv, u16* Op, int ldo,
;                   int q0, int nkt, const float* Fc, const unsigned* BM, float kmaxn, char* smem) {
;     ...
;     const bool diag = (MODE == 1) && (ts + 63 > qw);
;     float mx = -1e30f;
;     if (MODE == 1) {
; #pragma unroll
;       for (int k2 = 0; k2 < 2; ++k2)
; #pragma unroll
;         for (int j = 0; j < 4; ++j) {
;           const int kl = 32 * k2 + 16 * (j >> 1) + 8 * h + 4 * (j & 1);
;           const f32x4 f4 = *(const f32x4*)(sF + kl);
; #pragma unroll
;           for (int i = 0; i < 4; ++i) {
;             float x = sc[k2][j * 4 + i] * c1 + (fcq - f4[i]);
;             if (diag && (ts + kl + i > q)) x = -1e30f;
;             sc[k2][j * 4 + i] = x;
;             mx = fmaxf(mx, x);
;           }
;         }
;     } else {
; #pragma unroll
;       for (int k2 = 0; k2 < 2; ++k2)
; #pragma unroll
;         for (int e = 0; e < 16; ++e) mx = fmaxf(mx, sc[k2][e]);
;       mx *= c1;
;     }
;     mx = fmaxf(mx, shflx(mx, 32, lane));
;     if (__any(mx > m_run + 8.f)) {
;       const float m_new = fmaxf(m_run, mx);
;       const float alpha = __builtin_amdgcn_exp2f(m_run - m_new);
;       m_run = m_new; l_run *= alpha;
; #pragma unroll
;       for (int i = 0; i < 4; ++i)
; #pragma unroll
;         for (int e = 0; e < 16; ++e) o[i][e] *= alpha;
;     }
.Lfox_fast:
	s_mov_b32 s14, 0xf149f2ca
	s_waitcnt lgkmcnt(0)
	v_sub_f32_e32 v185, v141, v166
	v_fmac_f32_e32 v185, 0x3e0293ee, v66
	v_sub_f32_e32 v191, v141, v167
	v_fmac_f32_e32 v191, 0x3e0293ee, v67
	v_sub_f32_e32 v192, v141, v168
	v_fmac_f32_e32 v192, 0x3e0293ee, v68
	v_sub_f32_e32 v193, v141, v169
	v_fmac_f32_e32 v193, 0x3e0293ee, v69
	v_sub_f32_e32 v198, v141, v172
	v_fmac_f32_e32 v198, 0x3e0293ee, v70
	v_sub_f32_e32 v197, v141, v173
	v_fmac_f32_e32 v197, 0x3e0293ee, v71
	v_sub_f32_e32 v195, v141, v174
	v_fmac_f32_e32 v195, 0x3e0293ee, v72
	v_max3_f32 v66, v185, s14, v191
	v_sub_f32_e32 v196, v141, v175
	v_max3_f32 v66, v66, v192, v193
	v_fmac_f32_e32 v196, 0x3e0293ee, v73
	v_max3_f32 v66, v66, v198, v197
	v_max3_f32 v70, v66, v195, v196
	s_waitcnt lgkmcnt(0)
	v_sub_f32_e32 v184, v141, v212
	v_fmac_f32_e32 v184, 0x3e0293ee, v74
	v_sub_f32_e32 v183, v141, v213
	v_fmac_f32_e32 v183, 0x3e0293ee, v75
	v_sub_f32_e32 v182, v141, v214
	v_fmac_f32_e32 v182, 0x3e0293ee, v76
	v_sub_f32_e32 v179, v141, v215
	v_fmac_f32_e32 v179, 0x3e0293ee, v77
	v_max3_f32 v66, v70, v184, v183
	v_max3_f32 v70, v66, v182, v179
	s_waitcnt lgkmcnt(0)
	v_sub_f32_e32 v194, v141, v234
	v_fmac_f32_e32 v194, 0x3e0293ee, v78
	v_sub_f32_e32 v188, v141, v235
	v_fmac_f32_e32 v188, 0x3e0293ee, v79
	v_sub_f32_e32 v186, v141, v236
	v_fmac_f32_e32 v186, 0x3e0293ee, v80
	v_sub_f32_e32 v187, v141, v237
	v_fmac_f32_e32 v187, 0x3e0293ee, v81
	v_max3_f32 v66, v70, v194, v188
	v_max3_f32 v70, v66, v186, v187
	s_waitcnt lgkmcnt(0)
	v_sub_f32_e32 v176, v141, v238
	v_fmac_f32_e32 v176, 0x3e0293ee, v82
	v_sub_f32_e32 v175, v141, v239
	v_fmac_f32_e32 v175, 0x3e0293ee, v83
	v_sub_f32_e32 v174, v141, v240
	v_fmac_f32_e32 v174, 0x3e0293ee, v84
	v_sub_f32_e32 v173, v141, v241
	v_fmac_f32_e32 v173, 0x3e0293ee, v85
	v_max3_f32 v66, v70, v176, v175
	v_max3_f32 v70, v66, v174, v173
	s_waitcnt lgkmcnt(0)
	v_sub_f32_e32 v190, v141, v242
	v_fmac_f32_e32 v190, 0x3e0293ee, v86
	v_sub_f32_e32 v180, v141, v243
	v_fmac_f32_e32 v180, 0x3e0293ee, v87
	v_sub_f32_e32 v177, v141, v244
	v_fmac_f32_e32 v177, 0x3e0293ee, v88
	v_sub_f32_e32 v178, v141, v245
	v_fmac_f32_e32 v178, 0x3e0293ee, v89
	v_max3_f32 v66, v70, v190, v180
	v_max3_f32 v70, v66, v177, v178
	s_waitcnt lgkmcnt(0)
	v_sub_f32_e32 v169, v141, v246
	v_fmac_f32_e32 v169, 0x3e0293ee, v90
	v_sub_f32_e32 v168, v141, v247
	v_fmac_f32_e32 v168, 0x3e0293ee, v91
	v_sub_f32_e32 v167, v141, v248
	v_fmac_f32_e32 v167, 0x3e0293ee, v92
	v_sub_f32_e32 v166, v141, v249
	v_fmac_f32_e32 v166, 0x3e0293ee, v93
	v_max3_f32 v66, v70, v169, v168
	v_max3_f32 v70, v66, v167, v166
	v_add_u32_e32 v71, -11, v171
	s_waitcnt lgkmcnt(0)
	v_sub_f32_e32 v181, v141, v250
	v_fmac_f32_e32 v181, 0x3e0293ee, v94
	v_sub_f32_e32 v172, v141, v251
	v_fmac_f32_e32 v172, 0x3e0293ee, v95
	v_sub_f32_e32 v170, v141, v252
	v_fmac_f32_e32 v170, 0x3e0293ee, v96
	v_add_u32_e32 v68, -8, v171
	v_sub_f32_e32 v171, v141, v253
	v_fmac_f32_e32 v171, 0x3e0293ee, v97
	v_max3_f32 v66, v70, v181, v172
	v_max3_f32 v66, v66, v170, v171
	v_mov_b32_e32 v67, v66
	s_nop 1
	v_permlane32_swap_b32_e32 v67, v66
	s_nop 0
	v_max_f32_e32 v66, v66, v67
	v_add_f32_e32 v67, 0x41000000, v164
	v_cmp_gt_f32_e32 vcc, v66, v67
	s_cbranch_vccz .Lfox_f477
	v_max_f32_e32 v66, v66, v66
	v_max_f32_e32 v67, v164, v164
	v_max_f32_e32 v67, v67, v66
	v_sub_f32_e32 v66, v164, v67
	v_exp_f32_e32 v66, v66
	v_mov_b32_e32 v164, v67
	v_pk_mul_f32 v[64:65], v[64:65], v[66:67] op_sel_hi:[1,0]
	v_pk_mul_f32 v[62:63], v[62:63], v[66:67] op_sel_hi:[1,0]
	v_pk_mul_f32 v[60:61], v[60:61], v[66:67] op_sel_hi:[1,0]
	v_pk_mul_f32 v[58:59], v[58:59], v[66:67] op_sel_hi:[1,0]
	v_pk_mul_f32 v[56:57], v[56:57], v[66:67] op_sel_hi:[1,0]
	v_pk_mul_f32 v[54:55], v[54:55], v[66:67] op_sel_hi:[1,0]
	v_pk_mul_f32 v[52:53], v[52:53], v[66:67] op_sel_hi:[1,0]
	v_pk_mul_f32 v[50:51], v[50:51], v[66:67] op_sel_hi:[1,0]
	v_pk_mul_f32 v[48:49], v[48:49], v[66:67] op_sel_hi:[1,0]
	v_pk_mul_f32 v[46:47], v[46:47], v[66:67] op_sel_hi:[1,0]
	v_pk_mul_f32 v[44:45], v[44:45], v[66:67] op_sel_hi:[1,0]
	v_pk_mul_f32 v[42:43], v[42:43], v[66:67] op_sel_hi:[1,0]
	v_pk_mul_f32 v[40:41], v[40:41], v[66:67] op_sel_hi:[1,0]
	v_pk_mul_f32 v[38:39], v[38:39], v[66:67] op_sel_hi:[1,0]
	v_pk_mul_f32 v[36:37], v[36:37], v[66:67] op_sel_hi:[1,0]
	v_pk_mul_f32 v[34:35], v[34:35], v[66:67] op_sel_hi:[1,0]
	v_pk_mul_f32 v[32:33], v[32:33], v[66:67] op_sel_hi:[1,0]
	v_pk_mul_f32 v[30:31], v[30:31], v[66:67] op_sel_hi:[1,0]
	v_pk_mul_f32 v[28:29], v[28:29], v[66:67] op_sel_hi:[1,0]
	v_pk_mul_f32 v[26:27], v[26:27], v[66:67] op_sel_hi:[1,0]
	v_pk_mul_f32 v[24:25], v[24:25], v[66:67] op_sel_hi:[1,0]
	v_pk_mul_f32 v[22:23], v[22:23], v[66:67] op_sel_hi:[1,0]
	v_pk_mul_f32 v[20:21], v[20:21], v[66:67] op_sel_hi:[1,0]
	v_pk_mul_f32 v[18:19], v[18:19], v[66:67] op_sel_hi:[1,0]
	v_pk_mul_f32 v[16:17], v[16:17], v[66:67] op_sel_hi:[1,0]
	v_pk_mul_f32 v[14:15], v[14:15], v[66:67] op_sel_hi:[1,0]
	v_pk_mul_f32 v[12:13], v[12:13], v[66:67] op_sel_hi:[1,0]
	v_pk_mul_f32 v[10:11], v[10:11], v[66:67] op_sel_hi:[1,0]
	v_pk_mul_f32 v[8:9], v[8:9], v[66:67] op_sel_hi:[1,0]
	v_pk_mul_f32 v[6:7], v[6:7], v[66:67] op_sel_hi:[1,0]
	v_pk_mul_f32 v[4:5], v[4:5], v[66:67] op_sel_hi:[1,0]
	v_pk_mul_f32 v[2:3], v[2:3], v[66:67] op_sel_hi:[1,0]
	v_mul_f32_e32 v161, v161, v66

; template <int MODE>
; DI void attn_item(const u16* Qp, int ldq, const u16* Kp, int ldk, const u16* VTp, int ldv, u16* Op, int ldo,
;                   int q0, int nkt, const float* Fc, const unsigned* BM, float kmaxn, char* smem) {
;     ...
;     if (MODE == 2) bwn = *(const uint2*)(bmq + tn * 2);
;     AT_STAGE(kt + 3);
;     const bool diag = (MODE == 1) && (ts + 63 > qw);
;     float mx = -1e30f;
;     if (MODE == 1) {
; #pragma unroll
;       for (int k2 = 0; k2 < 2; ++k2)
; #pragma unroll
;         for (int j = 0; j < 4; ++j) {
;           const int kl = 32 * k2 + 16 * (j >> 1) + 8 * h + 4 * (j & 1);
;           const f32x4 f4 = *(const f32x4*)(sF + kl);
; #pragma unroll
;           for (int i = 0; i < 4; ++i) {
;             float x = sc[k2][j * 4 + i] * c1 + (fcq - f4[i]);
;             if (diag && (ts + kl + i > q)) x = -1e30f;
;             sc[k2][j * 4 + i] = x;
;             mx = fmaxf(mx, x);
;           }
;         }
;     } else {
; #pragma unroll
;       for (int k2 = 0; k2 < 2; ++k2)
; #pragma unroll
;         for (int e = 0; e < 16; ++e) mx = fmaxf(mx, sc[k2][e]);
;       mx *= c1;
;     }
;     mx = fmaxf(mx, shflx(mx, 32, lane));
;     if (__any(mx > m_run + 8.f)) {
;       const float m_new = fmaxf(m_run, mx);
;       const float alpha = __builtin_amdgcn_exp2f(m_run - m_new);
;       m_run = m_new; l_run *= alpha;
; #pragma unroll
;       for (int i = 0; i < 4; ++i)
; #pragma unroll
;         for (int e = 0; e < 16; ++e) o[i][e] *= alpha;
;     }
;     f32x16 sn[2];
;     float ps = 0.f;
; #pragma unroll
;     for (int g4 = 0; g4 < 4; ++g4) {
;       const int k2 = g4 >> 1, s2 = g4 & 1;
;       const f32x16 zero16 = {0.f, 0.f, 0.f, 0.f, 0.f, 0.f, 0.f, 0.f, 0.f, 0.f, 0.f, 0.f, 0.f, 0.f, 0.f, 0.f};
; #pragma unroll
;       for (int st = s2 * 4; st < s2 * 4 + 4; ++st) {
;         bf16x8 a = *(const bf16x8*)(sKn + kro + k2 * 8192 + (((st * 2 + h) ^ ksw) << 4));
;         sn[k2] = (st == 0) ? MFMA(a, qf[st], zero16) : MFMA(a, qf[st], sn[k2]);
;       }
;       const unsigned wbits = k2 ? bw.y : bw.x;
;       float pv8[8];
; #pragma unroll
;       for (int e8 = 0; e8 < 8; ++e8) {
;         const int e = 8 * s2 + e8;
;         float pv;
;         if (MODE == 1) {
;           const float x = sc[k2][e];
;           pv = __builtin_amdgcn_exp2f(x - m_run);
;           if (diag) pv = (x <= -1e29f) ? 0.f : pv;
;         } else {
.LBB0_492:
	s_mov_b32 s15, s13
	s_add_i32 s13, s13, 1
	s_cmp_lt_i32 s13, s12
	s_cselect_b32 s16, s13, s15
	s_lshl_b32 s36, s16, 1
	s_add_i32 s15, s15, 3
	s_and_b32 s16, s14, 0x18000
	s_min_i32 s15, s15, s11
	v_add_u32_e32 v0, s16, v171
	v_lshl_add_u64 v[2:3], s[36:37], 2, v[166:167]
	global_load_dwordx2 v[2:3], v[2:3], off
	v_mad_u64_u32 v[4:5], s[16:17], s15, v210, v[162:163]
	s_lshl_b32 s36, s15, 6
	v_readfirstlane_b32 s15, v0
	v_add_u32_e32 v8, 0x2000, v0
	s_mov_b32 m0, s15
	v_readfirstlane_b32 s15, v8
	global_load_lds_dwordx4 v[4:5], off
	v_lshl_add_u64 v[4:5], v[4:5], 0, s[18:19]
	s_mov_b32 m0, s15
	v_lshl_add_u64 v[6:7], s[36:37], 1, v[164:165]
	global_load_lds_dwordx4 v[4:5], off
	v_add_u32_e32 v4, 0x4000, v0
	v_add_u32_e32 v0, 0x6000, v0
	v_readfirstlane_b32 s15, v4
	s_mov_b32 m0, s15
	v_readfirstlane_b32 s15, v0
	v_lshl_add_u64 v[4:5], v[6:7], 0, s[20:21]
	global_load_lds_dwordx4 v[6:7], off
	s_mov_b32 m0, s15
	s_mov_b32 s15, 0xf149f2ca
	global_load_lds_dwordx4 v[4:5], off
	v_max3_f32 v0, v96, s15, v97
	v_max3_f32 v0, v0, v98, v99
	v_max3_f32 v0, v0, v100, v101
	v_max3_f32 v0, v0, v102, v103
	v_max3_f32 v0, v0, v104, v105
	v_max3_f32 v0, v0, v106, v107
	v_max3_f32 v0, v0, v108, v109
	v_max3_f32 v0, v0, v110, v111
	v_max3_f32 v0, v0, v80, v81
	v_max3_f32 v0, v0, v82, v83
	v_max3_f32 v0, v0, v84, v85
	v_max3_f32 v0, v0, v86, v87
	v_max3_f32 v0, v0, v88, v89
	v_max3_f32 v0, v0, v90, v91
	v_max3_f32 v0, v0, v92, v93
	v_max3_f32 v0, v0, v94, v95
	v_mul_f32_e32 v0, 0x3e0293ee, v0
	v_mov_b32_e32 v4, v0
	s_nop 1
	v_permlane32_swap_b32_e32 v4, v0
	s_nop 0
	v_max_f32_e32 v0, v0, v4
	v_add_f32_e32 v4, 0x41000000, v206
	v_cmp_gt_f32_e32 vcc, v0, v4
	s_cbranch_vccz .LBB0_494
	v_max_f32_e32 v0, v0, v0
	v_max_f32_e32 v4, v206, v206
	v_max_f32_e32 v4, v4, v0
	v_sub_f32_e32 v0, v206, v4
	v_exp_f32_e32 v0, v0
	v_mov_b32_e32 v206, v4
	v_pk_mul_f32 v[78:79], v[78:79], v[0:1] op_sel_hi:[1,0]
	v_pk_mul_f32 v[76:77], v[76:77], v[0:1] op_sel_hi:[1,0]
	v_pk_mul_f32 v[74:75], v[74:75], v[0:1] op_sel_hi:[1,0]
	v_pk_mul_f32 v[72:73], v[72:73], v[0:1] op_sel_hi:[1,0]
	v_pk_mul_f32 v[70:71], v[70:71], v[0:1] op_sel_hi:[1,0]
	v_pk_mul_f32 v[68:69], v[68:69], v[0:1] op_sel_hi:[1,0]
	v_pk_mul_f32 v[66:67], v[66:67], v[0:1] op_sel_hi:[1,0]
	v_pk_mul_f32 v[64:65], v[64:65], v[0:1] op_sel_hi:[1,0]
	v_pk_mul_f32 v[62:63], v[62:63], v[0:1] op_sel_hi:[1,0]
	v_pk_mul_f32 v[60:61], v[60:61], v[0:1] op_sel_hi:[1,0]
	v_pk_mul_f32 v[58:59], v[58:59], v[0:1] op_sel_hi:[1,0]
	v_pk_mul_f32 v[56:57], v[56:57], v[0:1] op_sel_hi:[1,0]
	v_pk_mul_f32 v[54:55], v[54:55], v[0:1] op_sel_hi:[1,0]
	v_pk_mul_f32 v[52:53], v[52:53], v[0:1] op_sel_hi:[1,0]
	v_pk_mul_f32 v[50:51], v[50:51], v[0:1] op_sel_hi:[1,0]
	v_pk_mul_f32 v[48:49], v[48:49], v[0:1] op_sel_hi:[1,0]
	v_pk_mul_f32 v[46:47], v[46:47], v[0:1] op_sel_hi:[1,0]
	v_pk_mul_f32 v[44:45], v[44:45], v[0:1] op_sel_hi:[1,0]
	v_pk_mul_f32 v[42:43], v[42:43], v[0:1] op_sel_hi:[1,0]
	v_pk_mul_f32 v[40:41], v[40:41], v[0:1] op_sel_hi:[1,0]
	v_pk_mul_f32 v[38:39], v[38:39], v[0:1] op_sel_hi:[1,0]
	v_pk_mul_f32 v[36:37], v[36:37], v[0:1] op_sel_hi:[1,0]
	v_pk_mul_f32 v[34:35], v[34:35], v[0:1] op_sel_hi:[1,0]
	v_pk_mul_f32 v[32:33], v[32:33], v[0:1] op_sel_hi:[1,0]
	v_pk_mul_f32 v[30:31], v[30:31], v[0:1] op_sel_hi:[1,0]
	v_pk_mul_f32 v[28:29], v[28:29], v[0:1] op_sel_hi:[1,0]
	v_pk_mul_f32 v[26:27], v[26:27], v[0:1] op_sel_hi:[1,0]
	v_pk_mul_f32 v[24:25], v[24:25], v[0:1] op_sel_hi:[1,0]
	v_pk_mul_f32 v[22:23], v[22:23], v[0:1] op_sel_hi:[1,0]
	v_pk_mul_f32 v[20:21], v[20:21], v[0:1] op_sel_hi:[1,0]
	v_pk_mul_f32 v[18:19], v[18:19], v[0:1] op_sel_hi:[1,0]
	v_pk_mul_f32 v[16:17], v[16:17], v[0:1] op_sel_hi:[1,0]
	v_mul_f32_e32 v182, v182, v0
.LBB0_494:
	s_add_i32 s15, s14, 0xffff0000
	s_and_b32 s15, s15, 0x18000
	v_add_u32_e32 v252, s15, v172
	s_add_i32 s15, s14, 0xfffe8000
	s_and_b32 s15, s15, 0x18000
	v_add_u32_e32 v211, s15, v204
	v_add_u32_e32 v203, v252, v173
	v_add_u32_e32 v205, v252, v174
	v_add_u32_e32 v207, v252, v175
	v_add_u32_e32 v209, v252, v176
	v_add_u32_e32 v217, v211, v190
	ds_read_b128 v[224:227], v203
	ds_read_b128 v[228:231], v205
	ds_read_b128 v[232:235], v207
	ds_read_b128 v[236:239], v209
	ds_read_b128 v[240:243], v217 offset:16384
	ds_read_b128 v[244:247], v217 offset:20480
	ds_read_b128 v[248:251], v217 offset:24576
	ds_read_b128 v[212:215], v217 offset:28672
	v_fma_f32 v0, v96, s33, -v206
	v_fma_f32 v14, v97, s33, -v206
	v_fma_f32 v96, v98, s33, -v206
	v_fma_f32 v98, v99, s33, -v206
	s_waitcnt lgkmcnt(7)
	v_mfma_f32_32x32x16_bf16 v[112:127], v[224:227], v[128:131], 0
	v_add_u32_e32 v216, v252, v177
	ds_read_b128 v[224:227], v216
	v_fma_f32 v100, v100, s33, -v206
	v_exp_f32_e32 v14, v14
	v_exp_f32_e32 v98, v98
	v_fma_f32 v101, v101, s33, -v206
	v_exp_f32_e32 v96, v96
	s_waitcnt lgkmcnt(7)
	v_mfma_f32_32x32x16_bf16 v[112:127], v[228:231], v[132:135], v[112:127]
	v_add_u32_e32 v216, v252, v178
	ds_read_b128 v[228:231], v216
	v_bfe_i32 v15, v168, v183, 1
	v_bfe_i32 v99, v168, v185, 1
	v_exp_f32_e32 v208, v0
	v_and_b32_e32 v14, v15, v14
	s_waitcnt lgkmcnt(7)
	v_mfma_f32_32x32x16_bf16 v[112:127], v[232:235], v[136:139], v[112:127]
	v_add_u32_e32 v216, v252, v179
	ds_read_b128 v[232:235], v216
	v_exp_f32_e32 v4, v100
	v_exp_f32_e32 v5, v101
	v_bfe_i32 v6, v168, v186, 1
	v_and_b32_e32 v15, v99, v98
	v_and_b32_e32 v98, v6, v4
	v_fma_f32 v4, v102, s33, -v206
	v_bfe_i32 v97, v168, v184, 1
	s_waitcnt lgkmcnt(7)
; #define MFMA(a, b, c) __builtin_amdgcn_mfma_f32_32x32x16_bf16((a), (b), (c), 0, 0, 0)
; template <int MODE>
; DI void attn_item(const u16* Qp, int ldq, const u16* Kp, int ldk, const u16* VTp, int ldv, u16* Op, int ldo,
;                   int q0, int nkt, const float* Fc, const unsigned* BM, float kmaxn, char* smem) {
;     ...
;     for (int g4 = 0; g4 < 4; ++g4) {
;       const int k2 = g4 >> 1, s2 = g4 & 1;
;       const f32x16 zero16 = {0.f, 0.f, 0.f, 0.f, 0.f, 0.f, 0.f, 0.f, 0.f, 0.f, 0.f, 0.f, 0.f, 0.f, 0.f, 0.f};
; #pragma unroll
;       for (int st = s2 * 4; st < s2 * 4 + 4; ++st) {
;         bf16x8 a = *(const bf16x8*)(sKn + kro + k2 * 8192 + (((st * 2 + h) ^ ksw) << 4));
;         sn[k2] = (st == 0) ? MFMA(a, qf[st], zero16) : MFMA(a, qf[st], sn[k2]);
;       }
;       const unsigned wbits = k2 ? bw.y : bw.x;
;       float pv8[8];
; #pragma unroll
;       for (int e8 = 0; e8 < 8; ++e8) {
;         const int e = 8 * s2 + e8;
;         float pv;
;         if (MODE == 1) {
;           const float x = sc[k2][e];
;           pv = __builtin_amdgcn_exp2f(x - m_run);
;           if (diag) pv = (x <= -1e29f) ? 0.f : pv;
;         } else {
;           pv = __builtin_amdgcn_exp2f(sc[k2][e] * c1 - m_run);
;           if (MODE == 2) {
;             const int kb = 16 * ((e >> 2) >> 1) + 8 * h + 4 * ((e >> 2) & 1) + (e & 3);
;             const int msk = __builtin_amdgcn_sbfe(wbits, kb, 1);
;             pv = __int_as_float(__float_as_int(pv) & msk);
;           }
;         }
;         pv8[e8] = pv; ps += pv;
;       }
;       u32x4 u;
;       u[0] = pk2(pv8[0], pv8[1]); u[1] = pk2(pv8[2], pv8[3]); u[2] = pk2(pv8[4], pv8[5]); u[3] = pk2(pv8[6], pv8[7]);
;       const bf16x8 pfg = __builtin_bit_cast(bf16x8, u);
; #pragma unroll
;       for (int dt = 0; dt < 4; ++dt) {
;         bf16x8 a = *(const bf16x8*)(sV + vro + dt * 4096 + (((4 * k2 + 2 * s2 + h) ^ vsw) << 4));
;         o[dt] = MFMA(a, pfg, o[dt]);
;       }
	v_mfma_f32_32x32x16_bf16 v[112:127], v[236:239], v[140:143], v[112:127]
	v_add_u32_e32 v216, v252, v180
	ds_read_b128 v[236:239], v216
	v_bfe_i32 v7, v168, v187, 1
	v_exp_f32_e32 v8, v4
	v_fma_f32 v4, v103, s33, -v206
	v_and_b32_e32 v96, v97, v96
	v_and_b32_e32 v97, v7, v5
	v_exp_f32_e32 v9, v4
	v_bfe_i32 v13, v168, v170, 1
	v_bfe_i32 v10, v168, v188, 1
	v_bfe_i32 v11, v168, v189, 1
	v_and_b32_e32 v13, v13, v208
	v_and_b32_e32 v100, v11, v9
	v_and_b32_e32 v101, v10, v8
	v_cvt_pk_bf16_f32 v8, v13, v14
	v_cvt_pk_bf16_f32 v9, v96, v15
	v_cvt_pk_bf16_f32 v10, v98, v97
	v_cvt_pk_bf16_f32 v11, v101, v100
	v_add_u32_e32 v217, v211, v199
	s_waitcnt lgkmcnt(7)
	s_nop 0
	v_mfma_f32_32x32x16_bf16 v[64:79], v[240:243], v[8:11], v[64:79]
	ds_read_b128 v[240:243], v217 offset:16384
	v_add_f32_e32 v4, 0, v13
	v_add_f32_e32 v4, v4, v14
	s_waitcnt lgkmcnt(7)
	v_mfma_f32_32x32x16_bf16 v[48:63], v[244:247], v[8:11], v[48:63]
	ds_read_b128 v[244:247], v217 offset:20480
	v_add_f32_e32 v4, v4, v96
	v_add_f32_e32 v4, v4, v15
	s_waitcnt lgkmcnt(7)
	v_mfma_f32_32x32x16_bf16 v[32:47], v[248:251], v[8:11], v[32:47]
	ds_read_b128 v[248:251], v217 offset:24576
	v_add_f32_e32 v4, v4, v98
	v_add_f32_e32 v4, v4, v97
	s_waitcnt lgkmcnt(7)
	v_mfma_f32_32x32x16_bf16 v[16:31], v[212:215], v[8:11], v[16:31]
	ds_read_b128 v[212:215], v217 offset:28672
	v_add_f32_e32 v4, v4, v101
	v_add_f32_e32 v96, v4, v100
	s_waitcnt lgkmcnt(7)
	v_mfma_f32_32x32x16_bf16 v[112:127], v[224:227], v[144:147], v[112:127]
	ds_read_b128 v[224:227], v203 offset:8192
	v_fma_f32 v8, v104, s33, -v206
	v_fma_f32 v10, v105, s33, -v206
	v_exp_f32_e32 v8, v8
	v_exp_f32_e32 v10, v10
	v_bfe_i32 v9, v168, v191, 1
	v_bfe_i32 v11, v168, v192, 1
	v_and_b32_e32 v98, v9, v8
	v_and_b32_e32 v97, v11, v10
	s_waitcnt lgkmcnt(7)
	v_mfma_f32_32x32x16_bf16 v[112:127], v[228:231], v[148:151], v[112:127]
	ds_read_b128 v[228:231], v205 offset:8192
	v_fma_f32 v8, v106, s33, -v206
	v_fma_f32 v10, v107, s33, -v206
	v_exp_f32_e32 v8, v8
	v_exp_f32_e32 v10, v10
	v_bfe_i32 v9, v168, v193, 1
	v_bfe_i32 v11, v168, v194, 1
	v_and_b32_e32 v100, v9, v8
	v_and_b32_e32 v99, v11, v10
	s_waitcnt lgkmcnt(7)
	v_mfma_f32_32x32x16_bf16 v[112:127], v[232:235], v[152:155], v[112:127]
	ds_read_b128 v[232:235], v207 offset:8192
	v_fma_f32 v8, v108, s33, -v206
	v_fma_f32 v10, v109, s33, -v206
	v_exp_f32_e32 v8, v8
	v_exp_f32_e32 v10, v10
	v_bfe_i32 v9, v168, v195, 1
	v_bfe_i32 v11, v168, v196, 1
	v_and_b32_e32 v101, v11, v10
	v_and_b32_e32 v102, v9, v8
	s_waitcnt lgkmcnt(7)
	v_mfma_f32_32x32x16_bf16 v[112:127], v[236:239], v[156:159], v[112:127]
	ds_read_b128 v[236:239], v209 offset:8192
	v_fma_f32 v8, v110, s33, -v206
	v_fma_f32 v10, v111, s33, -v206
	v_exp_f32_e32 v8, v8
	v_exp_f32_e32 v10, v10
	v_bfe_i32 v9, v168, v197, 1
	v_bfe_i32 v11, v168, v198, 1
	v_and_b32_e32 v104, v9, v8
	v_and_b32_e32 v103, v11, v10
	v_cvt_pk_bf16_f32 v8, v98, v97
	v_cvt_pk_bf16_f32 v9, v100, v99
	v_cvt_pk_bf16_f32 v10, v102, v101
	v_cvt_pk_bf16_f32 v11, v104, v103
	v_add_u32_e32 v217, v211, v200
	s_waitcnt lgkmcnt(7)
	s_nop 0
	v_mfma_f32_32x32x16_bf16 v[64:79], v[240:243], v[8:11], v[64:79]
	ds_read_b128 v[240:243], v217 offset:16384
	v_add_f32_e32 v253, v96, v98
	v_add_f32_e32 v253, v253, v97
	s_waitcnt lgkmcnt(7)
	v_mfma_f32_32x32x16_bf16 v[48:63], v[244:247], v[8:11], v[48:63]
	ds_read_b128 v[244:247], v217 offset:20480
	v_add_f32_e32 v253, v253, v100
	v_add_f32_e32 v253, v253, v99
	s_waitcnt lgkmcnt(7)
	v_mfma_f32_32x32x16_bf16 v[32:47], v[248:251], v[8:11], v[32:47]
	ds_read_b128 v[248:251], v217 offset:24576
	v_add_f32_e32 v253, v253, v102
	v_add_f32_e32 v253, v253, v101
	s_waitcnt lgkmcnt(7)
	v_mfma_f32_32x32x16_bf16 v[16:31], v[212:215], v[8:11], v[16:31]
	ds_read_b128 v[212:215], v217 offset:28672
	v_add_f32_e32 v253, v253, v104
	v_add_f32_e32 v168, v253, v103
	s_waitcnt lgkmcnt(7)
	v_mfma_f32_32x32x16_bf16 v[96:111], v[224:227], v[128:131], 0
	v_add_u32_e32 v216, v252, v177
	ds_read_b128 v[224:227], v216 offset:8192
	v_fma_f32 v8, v80, s33, -v206
	v_fma_f32 v10, v81, s33, -v206
	v_exp_f32_e32 v8, v8
	v_exp_f32_e32 v10, v10
	v_bfe_i32 v9, v169, v170, 1
	v_bfe_i32 v11, v169, v183, 1
	v_and_b32_e32 v81, v9, v8
	v_and_b32_e32 v80, v11, v10
	s_waitcnt lgkmcnt(7)
	v_mfma_f32_32x32x16_bf16 v[96:111], v[228:231], v[132:135], v[96:111]
	v_add_u32_e32 v216, v252, v178
	ds_read_b128 v[228:231], v216 offset:8192
	v_fma_f32 v8, v82, s33, -v206
	v_fma_f32 v10, v83, s33, -v206
	v_exp_f32_e32 v8, v8
	v_exp_f32_e32 v10, v10
	v_bfe_i32 v9, v169, v184, 1
	v_bfe_i32 v11, v169, v185, 1
	v_and_b32_e32 v83, v9, v8
	v_and_b32_e32 v82, v11, v10
	s_waitcnt lgkmcnt(7)
; template <int MODE>
; DI void attn_item(const u16* Qp, int ldq, const u16* Kp, int ldk, const u16* VTp, int ldv, u16* Op, int ldo,
;                   int q0, int nkt, const float* Fc, const unsigned* BM, float kmaxn, char* smem) {
;     ...
;     for (int g4 = 0; g4 < 4; ++g4) {
;       const int k2 = g4 >> 1, s2 = g4 & 1;
;       const f32x16 zero16 = {0.f, 0.f, 0.f, 0.f, 0.f, 0.f, 0.f, 0.f, 0.f, 0.f, 0.f, 0.f, 0.f, 0.f, 0.f, 0.f};
; #pragma unroll
;       for (int st = s2 * 4; st < s2 * 4 + 4; ++st) {
;         bf16x8 a = *(const bf16x8*)(sKn + kro + k2 * 8192 + (((st * 2 + h) ^ ksw) << 4));
;         sn[k2] = (st == 0) ? MFMA(a, qf[st], zero16) : MFMA(a, qf[st], sn[k2]);
;       }
;       const unsigned wbits = k2 ? bw.y : bw.x;
;       float pv8[8];
; #pragma unroll
;       for (int e8 = 0; e8 < 8; ++e8) {
;         const int e = 8 * s2 + e8;
;         float pv;
;         if (MODE == 1) {
;           const float x = sc[k2][e];
;           pv = __builtin_amdgcn_exp2f(x - m_run);
;           if (diag) pv = (x <= -1e29f) ? 0.f : pv;
;         } else {
;           pv = __builtin_amdgcn_exp2f(sc[k2][e] * c1 - m_run);
;           if (MODE == 2) {
;             const int kb = 16 * ((e >> 2) >> 1) + 8 * h + 4 * ((e >> 2) & 1) + (e & 3);
;             const int msk = __builtin_amdgcn_sbfe(wbits, kb, 1);
;             pv = __int_as_float(__float_as_int(pv) & msk);
;           }
;         }
;         pv8[e8] = pv; ps += pv;
;       }
;       u32x4 u;
;       u[0] = pk2(pv8[0], pv8[1]); u[1] = pk2(pv8[2], pv8[3]); u[2] = pk2(pv8[4], pv8[5]); u[3] = pk2(pv8[6], pv8[7]);
;       const bf16x8 pfg = __builtin_bit_cast(bf16x8, u);
; #pragma unroll
;       for (int dt = 0; dt < 4; ++dt) {
;         bf16x8 a = *(const bf16x8*)(sV + vro + dt * 4096 + (((4 * k2 + 2 * s2 + h) ^ vsw) << 4));
;         o[dt] = MFMA(a, pfg, o[dt]);
;       }
;       __builtin_amdgcn_sched_barrier(0);
;     }
;     l_run += ps;
;     asm volatile("s_waitcnt vmcnt(4)" ::: "memory");
;     if (MODE == 1 && tid < 16) *(f32x4*)(fct + ((kt + 1) & 3) * 64 + tid * 4) = rf;
;     if (MODE == 1) {
;       const int v = __all((qkb - flast) < (m_run - 160.f)) ? 1 : 0;
;       if (lane == 0) votes[(kt & 1) * 8 + wave] = v;
;     }
;     asm volatile("s_waitcnt lgkmcnt(0)" ::: "memory");
;     __builtin_amdgcn_s_barrier();
;     asm volatile("" ::: "memory");
;     sc[0] = sn[0]; sc[1] = sn[1]; bw = bwn;
	v_mfma_f32_32x32x16_bf16 v[96:111], v[232:235], v[136:139], v[96:111]
	v_add_u32_e32 v216, v252, v179
	ds_read_b128 v[232:235], v216 offset:8192
	v_fma_f32 v8, v84, s33, -v206
	v_fma_f32 v10, v85, s33, -v206
	v_exp_f32_e32 v8, v8
	v_exp_f32_e32 v10, v10
	v_bfe_i32 v9, v169, v186, 1
	v_bfe_i32 v11, v169, v187, 1
	v_and_b32_e32 v85, v9, v8
	v_and_b32_e32 v84, v11, v10
	s_waitcnt lgkmcnt(7)
	v_mfma_f32_32x32x16_bf16 v[96:111], v[236:239], v[140:143], v[96:111]
	v_add_u32_e32 v216, v252, v180
	ds_read_b128 v[236:239], v216 offset:8192
	v_fma_f32 v8, v86, s33, -v206
	v_fma_f32 v10, v87, s33, -v206
	v_exp_f32_e32 v8, v8
	v_exp_f32_e32 v10, v10
	v_bfe_i32 v9, v169, v188, 1
	v_bfe_i32 v11, v169, v189, 1
	v_and_b32_e32 v87, v9, v8
	v_and_b32_e32 v86, v11, v10
	v_cvt_pk_bf16_f32 v8, v81, v80
	v_cvt_pk_bf16_f32 v9, v83, v82
	v_cvt_pk_bf16_f32 v10, v85, v84
	v_cvt_pk_bf16_f32 v11, v87, v86
	v_add_u32_e32 v217, v211, v202
	s_waitcnt lgkmcnt(7)
	s_nop 0
	v_mfma_f32_32x32x16_bf16 v[64:79], v[240:243], v[8:11], v[64:79]
	ds_read_b128 v[240:243], v217 offset:16384
	v_add_f32_e32 v253, v168, v81
	v_add_f32_e32 v253, v253, v80
	s_waitcnt lgkmcnt(7)
	v_mfma_f32_32x32x16_bf16 v[48:63], v[244:247], v[8:11], v[48:63]
	ds_read_b128 v[244:247], v217 offset:20480
	v_add_f32_e32 v253, v253, v83
	v_add_f32_e32 v253, v253, v82
	s_waitcnt lgkmcnt(7)
	v_mfma_f32_32x32x16_bf16 v[32:47], v[248:251], v[8:11], v[32:47]
	ds_read_b128 v[248:251], v217 offset:24576
	v_add_f32_e32 v253, v253, v85
	v_add_f32_e32 v253, v253, v84
	s_waitcnt lgkmcnt(7)
	v_mfma_f32_32x32x16_bf16 v[16:31], v[212:215], v[8:11], v[16:31]
	ds_read_b128 v[212:215], v217 offset:28672
	v_add_f32_e32 v253, v253, v87
	v_add_f32_e32 v12, v253, v86
	s_waitcnt lgkmcnt(7)
	v_mfma_f32_32x32x16_bf16 v[96:111], v[224:227], v[144:147], v[96:111]
	v_fma_f32 v4, v88, s33, -v206
	v_fma_f32 v6, v89, s33, -v206
	v_exp_f32_e32 v4, v4
	v_exp_f32_e32 v6, v6
	v_bfe_i32 v5, v169, v191, 1
	v_bfe_i32 v7, v169, v192, 1
	v_and_b32_e32 v14, v5, v4
	v_and_b32_e32 v13, v7, v6
	s_waitcnt lgkmcnt(6)
	v_mfma_f32_32x32x16_bf16 v[96:111], v[228:231], v[148:151], v[96:111]
	v_fma_f32 v4, v90, s33, -v206
	v_fma_f32 v6, v91, s33, -v206
	v_exp_f32_e32 v4, v4
	v_exp_f32_e32 v6, v6
	v_bfe_i32 v5, v169, v193, 1
	v_bfe_i32 v7, v169, v194, 1
	v_and_b32_e32 v80, v5, v4
	v_and_b32_e32 v15, v7, v6
	s_waitcnt lgkmcnt(5)
	v_mfma_f32_32x32x16_bf16 v[96:111], v[232:235], v[152:155], v[96:111]
	v_fma_f32 v4, v92, s33, -v206
	v_fma_f32 v6, v93, s33, -v206
	v_exp_f32_e32 v4, v4
	v_exp_f32_e32 v6, v6
	v_bfe_i32 v5, v169, v195, 1
	v_bfe_i32 v7, v169, v196, 1
	v_and_b32_e32 v82, v5, v4
	v_and_b32_e32 v81, v7, v6
	s_waitcnt lgkmcnt(4)
	v_mfma_f32_32x32x16_bf16 v[96:111], v[236:239], v[156:159], v[96:111]
	v_fma_f32 v4, v94, s33, -v206
	v_fma_f32 v6, v95, s33, -v206
	v_exp_f32_e32 v4, v4
	v_exp_f32_e32 v6, v6
	v_bfe_i32 v5, v169, v197, 1
	v_bfe_i32 v7, v169, v198, 1
	v_and_b32_e32 v84, v5, v4
	v_and_b32_e32 v83, v7, v6
	v_cvt_pk_bf16_f32 v4, v14, v13
	v_cvt_pk_bf16_f32 v5, v80, v15
	v_cvt_pk_bf16_f32 v6, v82, v81
	v_cvt_pk_bf16_f32 v7, v84, v83
	s_waitcnt lgkmcnt(3)
	s_nop 0
	v_mfma_f32_32x32x16_bf16 v[64:79], v[240:243], v[4:7], v[64:79]
	s_waitcnt lgkmcnt(2)
	v_mfma_f32_32x32x16_bf16 v[48:63], v[244:247], v[4:7], v[48:63]
	s_waitcnt lgkmcnt(1)
	v_mfma_f32_32x32x16_bf16 v[32:47], v[248:251], v[4:7], v[32:47]
	v_add_f32_e32 v0, v12, v14
	v_add_f32_e32 v0, v0, v13
	v_add_f32_e32 v0, v0, v80
	v_add_f32_e32 v0, v0, v15
	v_add_f32_e32 v0, v0, v82
	v_add_f32_e32 v0, v0, v81
	s_waitcnt lgkmcnt(0)
	v_mfma_f32_32x32x16_bf16 v[16:31], v[212:215], v[4:7], v[16:31]
	v_add_f32_e32 v0, v0, v84
	v_add_f32_e32 v0, v0, v83
	s_waitcnt vmcnt(4)
	s_waitcnt lgkmcnt(0)
	v_add_f32_e32 v182, v182, v0
	v_mov_b64_e32 v[80:81], v[96:97]
	v_mov_b64_e32 v[82:83], v[98:99]
	v_mov_b64_e32 v[84:85], v[100:101]
	v_mov_b64_e32 v[86:87], v[102:103]
	v_mov_b64_e32 v[88:89], v[104:105]
	v_mov_b64_e32 v[90:91], v[106:107]
	v_mov_b64_e32 v[92:93], v[108:109]
	v_mov_b64_e32 v[94:95], v[110:111]
	v_mov_b64_e32 v[96:97], v[112:113]
	v_mov_b64_e32 v[98:99], v[114:115]
	v_mov_b64_e32 v[100:101], v[116:117]
	v_mov_b64_e32 v[102:103], v[118:119]
	v_mov_b64_e32 v[104:105], v[120:121]
	v_mov_b64_e32 v[106:107], v[122:123]
	v_mov_b64_e32 v[108:109], v[124:125]
	v_mov_b64_e32 v[110:111], v[126:127]
	v_mov_b64_e32 v[168:169], v[2:3]
	s_barrier
	s_add_i32 s14, s14, 0x8000
	s_cmp_lg_u32 s12, s13
	s_cbranch_scc0 .LBB0_489
	s_branch .LBB0_492
